# B-out GEMM re-partitioned: 256 units of 272 rows (256-row template tile + hand-written 16-row slab with direct global->MFMA operands), no second round
# baseline (speedup 1.0000x reference)
.LBB0_1053:
	s_or_b64 exec, exec, s[38:39]
	v_readlane_b32 s0, v255, 1
	s_mov_b64 s[6:7], s[96:97]
	v_mov_b32_e32 v8, v201
	v_readlane_b32 s1, v255, 2
	s_waitcnt lgkmcnt(0)
	s_barrier
	s_and_b64 vcc, exec, s[0:1]
	v_readfirstlane_b32 s5, v8
	s_cbranch_vccnz .LBB0_1069
	v_lshlrev_b32_e32 v0, 4, v8
	v_add_u32_e32 v1, 0x2000, v0
	v_ashrrev_i32_e32 v2, 31, v1
	v_lshrrev_b32_e32 v2, 22, v2
	v_add_u32_e32 v2, v1, v2
	v_ashrrev_i32_e32 v9, 10, v2
	v_mul_i32_i24_e32 v3, 0x400, v9
	v_sub_u32_e32 v1, v1, v3
	v_lshrrev_b32_e32 v3, 4, v1
	s_load_dwordx4 s[8:11], s[6:7], 0xb8
	v_bitop3_b32 v1, v3, v1, 32 bitop3:0x6c
	v_ashrrev_i32_e32 v3, 31, v1
	v_lshrrev_b32_e32 v3, 26, v3
	v_add_u32_e32 v3, v1, v3
	v_ashrrev_i32_e32 v10, 6, v3
	v_and_b32_e32 v3, 0xc0, v3
	s_waitcnt lgkmcnt(0)
	s_add_u32 s0, s10, 0x32752000
	v_sub_u32_e32 v1, v1, v3
	v_mov_b32_e32 v3, 1
	s_addc_u32 s1, s11, 0
	v_lshlrev_b32_e32 v2, 5, v9
	v_ashrrev_i16_sdwa v1, v3, sext(v1) dst_sel:DWORD dst_unused:UNUSED_PAD src0_sel:DWORD src1_sel:BYTE_0
	s_add_u32 s34, s10, 0x3600000
	v_and_b32_e32 v2, 32, v2
	v_bfe_i32 v11, v1, 0, 16
	s_addc_u32 s35, s11, 0
	v_add_u32_e32 v1, v2, v11
	v_lshlrev_b32_e32 v2, 3, v9
	s_lshr_b32 s4, s3, 29
	v_and_b32_e32 v2, 0xffff0, v2
	s_add_i32 s4, s2, s4
	s_ashr_i32 s12, s5, 6
	v_add_lshl_u32 v2, v10, v2, 12
	s_ashr_i32 s6, s4, 3
	s_and_b32 s4, s4, -8
	s_ashr_i32 s14, s5, 8
	s_lshl_b32 s36, s12, 10
	v_lshl_add_u32 v128, v1, 1, v2
	v_bfe_i32 v2, v8, 27, 1
	s_sub_i32 s4, s2, s4
	v_lshrrev_b32_e32 v2, 22, v2
	s_cmp_lt_i32 s4, 0
	v_add_u32_e32 v2, v0, v2
	s_cselect_b32 s7, 35, 34
	v_and_b32_e32 v2, 0xfffffc00, v2
	s_mul_i32 s4, s4, s7
	v_sub_u32_e32 v0, v0, v2
	s_add_i32 s4, s4, s6
	v_lshrrev_b32_e32 v2, 4, v0
	s_ashr_i32 s6, s4, 31
	v_bitop3_b32 v2, v2, v0, 32 bitop3:0x6c
	v_ashrrev_i32_e32 v0, 31, v0
	s_lshr_b32 s6, s6, 27
	v_lshrrev_b32_e32 v0, 26, v0
	s_add_i32 s6, s4, s6
	v_ashrrev_i32_e32 v1, 31, v8
	v_add_u32_e32 v0, v2, v0
	s_ashr_i32 s7, s6, 5
	v_lshrrev_b32_e32 v1, 26, v1
	v_ashrrev_i32_e32 v13, 6, v0
	s_lshl_b32 s13, s7, 3
	v_add_u32_e32 v1, v8, v1
	v_mul_i32_i24_e32 v0, 64, v13
	s_sub_i32 s7, 0x44, s13
	v_ashrrev_i32_e32 v12, 6, v1
	v_sub_u32_e32 v0, v2, v0
	s_min_u32 s15, s7, 8
	s_andn2_b32 s6, s6, 31
	v_lshlrev_b32_e32 v1, 5, v12
	v_ashrrev_i16_sdwa v0, v3, sext(v0) dst_sel:DWORD dst_unused:UNUSED_PAD src0_sel:DWORD src1_sel:BYTE_0
	s_sub_i32 s16, s4, s6
	v_cvt_f32_ubyte0_e32 v3, s15
	v_and_b32_e32 v1, 32, v1
	v_bfe_i32 v14, v0, 0, 16
	v_cvt_f32_i32_e32 v2, s16
	v_rcp_iflag_f32_e32 v4, v3
	v_add_u32_e32 v0, v1, v14
	v_lshlrev_b32_e32 v1, 3, v12
	v_and_b32_e32 v1, 0xffff0, v1
	v_add_lshl_u32 v1, v13, v1, 12
	v_lshl_add_u32 v130, v0, 1, v1
	v_mul_f32_e32 v0, v2, v4
	v_trunc_f32_e32 v0, v0
	v_fma_f32 v1, -v0, v3, v2
	v_cvt_i32_f32_e32 v0, v0
	s_ashr_i32 s4, s16, 30
	s_or_b32 s4, s4, 1
	v_cmp_ge_f32_e64 s[6:7], |v1|, v3
	s_and_b64 s[6:7], s[6:7], exec
	s_cselect_b32 s4, s4, 0
	v_readfirstlane_b32 s6, v0
	s_add_i32 s4, s6, s4
	s_mul_i32 s6, s4, s15
	s_sub_i32 s6, s16, s6
	s_sext_i32_i8 s6, s6
	s_add_i32 s24, s13, s6
	s_and_b32 s24, s2, 7
	s_lshr_b32 s4, s2, 3
	s_lshl_b32 s24, s24, 3
	s_lshr_b32 s6, s4, 2
	s_add_i32 s24, s24, s6
	s_and_b32 s4, s4, 3
	s_ashr_i32 s25, s24, 31
	s_bfe_i64 s[16:17], s[4:5], 0x80000
	s_mul_i32 s6, s24, 0x110000
	s_mov_b32 s7, 0
	s_lshl_b64 s[16:17], s[16:17], 20
	s_add_u32 s26, s34, s16
	s_addc_u32 s27, s35, s17
	s_add_i32 s25, s36, 0
	s_add_i32 m0, s25, 0x10000
	v_mov_b32_e32 v131, 0
	global_load_lds_dwordx4 v130, s[26:27]
	s_add_i32 m0, s25, 0x12000
	s_add_u32 s16, s26, 0x80000
	global_load_lds_dwordx4 v128, s[26:27]
	s_addc_u32 s17, s27, 0
	s_add_i32 m0, s25, 0x14000
	v_mov_b32_e32 v129, v131
	global_load_lds_dwordx4 v130, s[16:17]
	s_add_i32 m0, s25, 0x16000
	s_add_u32 s28, s0, s6
	s_addc_u32 s29, s1, s7
	s_add_i32 s37, s25, 0x2000
	global_load_lds_dwordx4 v128, s[16:17]
	s_mov_b32 m0, s25
	s_add_u32 s6, s28, 0x80000
	global_load_lds_dwordx4 v130, s[28:29]
	s_mov_b32 m0, s37
	s_addc_u32 s7, s29, 0
	s_add_i32 s38, s25, 0x4000
	global_load_lds_dwordx4 v128, s[28:29]
	s_mov_b32 m0, s38
	s_add_i32 s39, s25, 0x6000
	global_load_lds_dwordx4 v130, s[6:7]
	s_mov_b32 m0, s39
	s_cmp_eq_u32 s14, 1
	global_load_lds_dwordx4 v128, s[6:7]
	s_mov_b32 s40, 0
	v_lshl_add_u64 v[6:7], s[26:27], 0, v[130:131]
	v_lshl_add_u64 v[4:5], s[26:27], 0, v[128:129]
	v_lshl_add_u64 v[0:1], s[28:29], 0, v[130:131]
	s_cselect_b64 s[6:7], -1, 0
	s_cmp_lg_u32 s14, 1
	v_lshl_add_u64 v[2:3], s[28:29], 0, v[128:129]
	s_cbranch_scc1 .LBB0_1056
	s_barrier
.LBB0_1056:
	s_add_u32 s10, s10, 0x36b52000
	s_addc_u32 s11, s11, 0
	s_lshl_b32 s12, s12, 5
	s_and_b32 s18, s12, 0x60
	s_mov_b64 s[12:13], 0x80
	s_add_i32 m0, s25, 0x18000
	v_lshl_add_u64 v[6:7], v[6:7], 0, s[12:13]
	s_lshl_b32 s15, s14, 13
	s_lshl_b32 s19, s18, 7
	s_waitcnt vmcnt(2)
	s_barrier
	global_load_lds_dwordx4 v[6:7], off
	v_lshl_add_u64 v[4:5], v[4:5], 0, s[12:13]
	s_add_i32 m0, s25, 0x1a000
	s_add_i32 s41, s25, 0x8000
	s_add_i32 s42, s25, 0xa000
	global_load_lds_dwordx4 v[4:5], off
	v_lshl_add_u64 v[0:1], v[0:1], 0, s[12:13]
	s_mov_b32 m0, s41
	s_add_u32 s16, s26, 0x80080
	global_load_lds_dwordx4 v[0:1], off
	v_lshl_add_u64 v[0:1], v[2:3], 0, s[12:13]
	s_mov_b32 m0, s42
	s_addc_u32 s17, s27, 0
	global_load_lds_dwordx4 v[0:1], off
	s_add_i32 m0, s25, 0x1c000
	v_lshl_add_u64 v[0:1], s[16:17], 0, v[130:131]
	global_load_lds_dwordx4 v[0:1], off
	v_lshl_add_u64 v[0:1], s[16:17], 0, v[128:129]
	s_add_i32 m0, s25, 0x1e000
	s_cmpk_lt_u32 s5, 0x100
	global_load_lds_dwordx4 v[0:1], off
	v_bfe_u32 v1, v8, 4, 2
	v_and_b32_e32 v0, 15, v8
	v_lshlrev_b32_e32 v2, 4, v1
	v_lshl_or_b32 v144, s14, 6, v0
	v_lshl_or_b32 v0, v0, 6, v2
	v_lshlrev_b32_e32 v2, 2, v8
	v_and_b32_e32 v2, 32, v2
	v_bitop3_b32 v3, v0, s15, v2 bitop3:0xde
	v_bitop3_b32 v145, v0, s19, v2 bitop3:0xde
	v_lshlrev_b32_e32 v0, 15, v9
	v_and_b32_e32 v0, 0xffff0000, v0
	v_lshl_or_b32 v146, v1, 2, s18
	v_lshl_add_u32 v0, v10, 12, v0
	v_and_b32_e32 v1, 1, v9
	v_lshl_or_b32 v0, v1, 6, v0
	v_lshl_add_u32 v132, v11, 1, v0
	v_lshlrev_b32_e32 v0, 15, v12
	v_and_b32_e32 v0, 0xffff0000, v0
	s_waitcnt vmcnt(6)
	v_lshl_add_u32 v0, v13, 12, v0
	v_and_b32_e32 v1, 1, v12
	s_cselect_b64 s[14:15], -1, 0
	v_lshl_or_b32 v0, v1, 6, v0
	s_add_i32 s43, 0, 0x10000
	s_add_i32 s44, 0, 0x14000
	s_sext_i32_i8 s46, s4
	v_mov_b32_e32 v133, v131
	v_lshl_add_u32 v134, v14, 1, v0
	v_mov_b32_e32 v135, v131
	v_mov_b64_e32 v[136:137], 0
	v_mov_b64_e32 v[138:139], 0
	v_add_u32_e32 v147, s43, v145
	v_add_u32_e32 v148, s44, v145
	v_add_u32_e32 v149, 0, v3
	s_movk_i32 s45, 0x4400
	s_barrier
	s_branch .LBB0_1059

.LBB0_1065:
	s_mul_i32 s60, s24, 0x110
	v_add_u32_e32 v142, s60, v144
	v_ashrrev_i32_e32 v143, 31, v142
	v_cmp_gt_i32_e32 vcc, s45, v142
	v_add_u32_e32 v141, 0xffffbc00, v142
	v_lshl_or_b32 v140, s46, 8, v146
	v_cndmask_b32_e32 v143, 0, v143, vcc
	v_cndmask_b32_e32 v150, v141, v142, vcc
	v_mov_b32_e32 v151, v143
	v_lshlrev_b64 v[150:151], 12, v[150:151]
	v_ashrrev_i32_e32 v141, 31, v140
	v_lshl_add_u64 v[150:151], s[10:11], 0, v[150:151]
	v_lshlrev_b64 v[140:141], 2, v[140:141]
	v_lshl_add_u64 v[154:155], v[150:151], 0, v[140:141]
	flat_load_dwordx4 v[150:153], v[154:155]
	v_lshlrev_b64 v[156:157], 12, v[142:143]
	v_lshl_add_u64 v[156:157], s[8:9], 0, v[156:157]
	v_lshl_add_u64 v[156:157], v[156:157], 0, v[140:141]
	s_waitcnt vmcnt(0) lgkmcnt(0)
	v_pk_add_f32 v[126:127], v[126:127], v[152:153]
	v_pk_add_f32 v[124:125], v[124:125], v[150:151]
	flat_store_dwordx4 v[156:157], v[124:127]
	flat_load_dwordx4 v[124:127], v[154:155] offset:64
	s_waitcnt vmcnt(0) lgkmcnt(0)
	v_pk_add_f32 v[122:123], v[122:123], v[126:127]
	v_pk_add_f32 v[120:121], v[120:121], v[124:125]
	flat_store_dwordx4 v[156:157], v[120:123] offset:64
	flat_load_dwordx4 v[120:123], v[154:155] offset:512
	s_waitcnt vmcnt(0) lgkmcnt(0)
	v_pk_add_f32 v[118:119], v[118:119], v[122:123]
	v_pk_add_f32 v[116:117], v[116:117], v[120:121]
	flat_store_dwordx4 v[156:157], v[116:119] offset:512
	flat_load_dwordx4 v[116:119], v[154:155] offset:576
	v_add_u32_e32 v120, 16, v142
	v_ashrrev_i32_e32 v121, 31, v120
	v_cmp_gt_i32_e32 vcc, s45, v120
	v_add_u32_e32 v122, 0xffffbc10, v142
	s_waitcnt vmcnt(0) lgkmcnt(0)
	v_pk_add_f32 v[110:111], v[110:111], v[118:119]
	v_cndmask_b32_e32 v121, 0, v121, vcc
	v_cndmask_b32_e32 v122, v122, v120, vcc
	v_mov_b32_e32 v123, v121
	v_lshlrev_b64 v[122:123], 12, v[122:123]
	v_lshl_add_u64 v[122:123], s[10:11], 0, v[122:123]
	v_pk_add_f32 v[108:109], v[108:109], v[116:117]
	v_lshl_add_u64 v[122:123], v[122:123], 0, v[140:141]
	flat_store_dwordx4 v[156:157], v[108:111] offset:576
	flat_load_dwordx4 v[108:111], v[122:123]
	v_lshlrev_b64 v[116:117], 12, v[120:121]
	v_lshl_add_u64 v[116:117], s[8:9], 0, v[116:117]
	v_lshl_add_u64 v[116:117], v[116:117], 0, v[140:141]
	s_waitcnt vmcnt(0) lgkmcnt(0)
	v_pk_add_f32 v[110:111], v[114:115], v[110:111]
	v_pk_add_f32 v[108:109], v[112:113], v[108:109]
	flat_store_dwordx4 v[116:117], v[108:111]
	flat_load_dwordx4 v[108:111], v[122:123] offset:64
	s_waitcnt vmcnt(0) lgkmcnt(0)
	v_pk_add_f32 v[106:107], v[106:107], v[110:111]
	v_pk_add_f32 v[104:105], v[104:105], v[108:109]
	flat_store_dwordx4 v[116:117], v[104:107] offset:64
	flat_load_dwordx4 v[104:107], v[122:123] offset:512
	s_waitcnt vmcnt(0) lgkmcnt(0)
	v_pk_add_f32 v[102:103], v[102:103], v[106:107]
	v_pk_add_f32 v[100:101], v[100:101], v[104:105]
	flat_store_dwordx4 v[116:117], v[100:103] offset:512
	flat_load_dwordx4 v[100:103], v[122:123] offset:576
	v_add_u32_e32 v104, 32, v142
	v_ashrrev_i32_e32 v105, 31, v104
	v_cmp_gt_i32_e32 vcc, s45, v104
	v_add_u32_e32 v106, 0xffffbc20, v142
	s_waitcnt vmcnt(0) lgkmcnt(0)
	v_pk_add_f32 v[94:95], v[94:95], v[102:103]
	v_cndmask_b32_e32 v105, 0, v105, vcc
	v_cndmask_b32_e32 v106, v106, v104, vcc
	v_mov_b32_e32 v107, v105
	v_lshlrev_b64 v[106:107], 12, v[106:107]
	v_lshl_add_u64 v[106:107], s[10:11], 0, v[106:107]
	v_pk_add_f32 v[92:93], v[92:93], v[100:101]
	v_lshl_add_u64 v[106:107], v[106:107], 0, v[140:141]
	flat_store_dwordx4 v[116:117], v[92:95] offset:576
	flat_load_dwordx4 v[92:95], v[106:107]
	v_lshlrev_b64 v[100:101], 12, v[104:105]
	v_lshl_add_u64 v[100:101], s[8:9], 0, v[100:101]
	v_lshl_add_u64 v[100:101], v[100:101], 0, v[140:141]
	s_waitcnt vmcnt(0) lgkmcnt(0)
	v_pk_add_f32 v[94:95], v[98:99], v[94:95]
	v_pk_add_f32 v[92:93], v[96:97], v[92:93]
	flat_store_dwordx4 v[100:101], v[92:95]
	flat_load_dwordx4 v[92:95], v[106:107] offset:64
	s_waitcnt vmcnt(0) lgkmcnt(0)
	v_pk_add_f32 v[90:91], v[90:91], v[94:95]
	v_pk_add_f32 v[88:89], v[88:89], v[92:93]
	flat_store_dwordx4 v[100:101], v[88:91] offset:64
	flat_load_dwordx4 v[88:91], v[106:107] offset:512
	s_waitcnt vmcnt(0) lgkmcnt(0)
	v_pk_add_f32 v[86:87], v[86:87], v[90:91]
	v_pk_add_f32 v[84:85], v[84:85], v[88:89]
	flat_store_dwordx4 v[100:101], v[84:87] offset:512
	flat_load_dwordx4 v[84:87], v[106:107] offset:576
	v_add_u32_e32 v88, 48, v142
	v_ashrrev_i32_e32 v89, 31, v88
	v_cmp_gt_i32_e32 vcc, s45, v88
	v_add_u32_e32 v90, 0xffffbc30, v142
	s_waitcnt vmcnt(0) lgkmcnt(0)
	v_pk_add_f32 v[78:79], v[78:79], v[86:87]
	v_cndmask_b32_e32 v89, 0, v89, vcc
	v_cndmask_b32_e32 v90, v90, v88, vcc
	v_mov_b32_e32 v91, v89
	v_lshlrev_b64 v[90:91], 12, v[90:91]
	v_lshl_add_u64 v[90:91], s[10:11], 0, v[90:91]
	v_pk_add_f32 v[76:77], v[76:77], v[84:85]
	v_lshl_add_u64 v[90:91], v[90:91], 0, v[140:141]
	flat_store_dwordx4 v[100:101], v[76:79] offset:576
	flat_load_dwordx4 v[76:79], v[90:91]
	v_lshlrev_b64 v[84:85], 12, v[88:89]
	v_lshl_add_u64 v[84:85], s[8:9], 0, v[84:85]
	v_lshl_add_u64 v[84:85], v[84:85], 0, v[140:141]
	s_waitcnt vmcnt(0) lgkmcnt(0)
	v_pk_add_f32 v[78:79], v[82:83], v[78:79]
	v_pk_add_f32 v[76:77], v[80:81], v[76:77]
	flat_store_dwordx4 v[84:85], v[76:79]
	flat_load_dwordx4 v[76:79], v[90:91] offset:64
	s_waitcnt vmcnt(0) lgkmcnt(0)
	v_pk_add_f32 v[74:75], v[74:75], v[78:79]
	v_pk_add_f32 v[72:73], v[72:73], v[76:77]
	flat_store_dwordx4 v[84:85], v[72:75] offset:64
	flat_load_dwordx4 v[72:75], v[90:91] offset:512
	s_waitcnt vmcnt(0) lgkmcnt(0)
	v_pk_add_f32 v[70:71], v[70:71], v[74:75]
	v_pk_add_f32 v[68:69], v[68:69], v[72:73]
	flat_store_dwordx4 v[84:85], v[68:71] offset:512
	flat_load_dwordx4 v[68:71], v[90:91] offset:576
	v_add_u32_e32 v72, 0x80, v142
	v_ashrrev_i32_e32 v73, 31, v72
	v_cmp_gt_i32_e32 vcc, s45, v72
	v_add_u32_e32 v74, 0xffffbc80, v142
	s_waitcnt vmcnt(0) lgkmcnt(0)
	v_pk_add_f32 v[66:67], v[66:67], v[70:71]
	v_cndmask_b32_e32 v73, 0, v73, vcc
	v_cndmask_b32_e32 v74, v74, v72, vcc
	v_mov_b32_e32 v75, v73
	v_lshlrev_b64 v[74:75], 12, v[74:75]
	v_lshl_add_u64 v[74:75], s[10:11], 0, v[74:75]
	v_pk_add_f32 v[64:65], v[64:65], v[68:69]
	v_lshl_add_u64 v[74:75], v[74:75], 0, v[140:141]
	flat_store_dwordx4 v[84:85], v[64:67] offset:576
	flat_load_dwordx4 v[64:67], v[74:75]
	v_lshlrev_b64 v[68:69], 12, v[72:73]
	v_lshl_add_u64 v[68:69], s[8:9], 0, v[68:69]
	v_lshl_add_u64 v[68:69], v[68:69], 0, v[140:141]
	s_waitcnt vmcnt(0) lgkmcnt(0)
	v_pk_add_f32 v[62:63], v[62:63], v[66:67]
	v_pk_add_f32 v[60:61], v[60:61], v[64:65]
	flat_store_dwordx4 v[68:69], v[60:63]
	flat_load_dwordx4 v[60:63], v[74:75] offset:64
	s_waitcnt vmcnt(0) lgkmcnt(0)
	v_pk_add_f32 v[58:59], v[58:59], v[62:63]
	v_pk_add_f32 v[56:57], v[56:57], v[60:61]
	flat_store_dwordx4 v[68:69], v[56:59] offset:64
	flat_load_dwordx4 v[56:59], v[74:75] offset:512
	s_waitcnt vmcnt(0) lgkmcnt(0)
	v_pk_add_f32 v[54:55], v[54:55], v[58:59]
	v_pk_add_f32 v[52:53], v[52:53], v[56:57]
	flat_store_dwordx4 v[68:69], v[52:55] offset:512
	flat_load_dwordx4 v[52:55], v[74:75] offset:576
	v_add_u32_e32 v56, 0x90, v142
	v_ashrrev_i32_e32 v57, 31, v56
	v_cmp_gt_i32_e32 vcc, s45, v56
	v_add_u32_e32 v58, 0xffffbc90, v142
	s_waitcnt vmcnt(0) lgkmcnt(0)
	v_pk_add_f32 v[46:47], v[46:47], v[54:55]
	v_cndmask_b32_e32 v57, 0, v57, vcc
	v_cndmask_b32_e32 v58, v58, v56, vcc
	v_mov_b32_e32 v59, v57
	v_lshlrev_b64 v[58:59], 12, v[58:59]
	v_lshl_add_u64 v[58:59], s[10:11], 0, v[58:59]
	v_pk_add_f32 v[44:45], v[44:45], v[52:53]
	v_lshl_add_u64 v[58:59], v[58:59], 0, v[140:141]
	flat_store_dwordx4 v[68:69], v[44:47] offset:576
	flat_load_dwordx4 v[44:47], v[58:59]
	v_lshlrev_b64 v[52:53], 12, v[56:57]
	v_lshl_add_u64 v[52:53], s[8:9], 0, v[52:53]
	v_lshl_add_u64 v[52:53], v[52:53], 0, v[140:141]
	s_waitcnt vmcnt(0) lgkmcnt(0)
	v_pk_add_f32 v[46:47], v[50:51], v[46:47]
	v_pk_add_f32 v[44:45], v[48:49], v[44:45]
	flat_store_dwordx4 v[52:53], v[44:47]
	flat_load_dwordx4 v[44:47], v[58:59] offset:64
	s_waitcnt vmcnt(0) lgkmcnt(0)
	v_pk_add_f32 v[42:43], v[42:43], v[46:47]
	v_pk_add_f32 v[40:41], v[40:41], v[44:45]
	flat_store_dwordx4 v[52:53], v[40:43] offset:64
	flat_load_dwordx4 v[40:43], v[58:59] offset:512
	s_waitcnt vmcnt(0) lgkmcnt(0)
	v_pk_add_f32 v[38:39], v[38:39], v[42:43]
	v_pk_add_f32 v[36:37], v[36:37], v[40:41]
	flat_store_dwordx4 v[52:53], v[36:39] offset:512
	flat_load_dwordx4 v[36:39], v[58:59] offset:576
	v_add_u32_e32 v40, 0xa0, v142
	v_ashrrev_i32_e32 v41, 31, v40
	v_cmp_gt_i32_e32 vcc, s45, v40
	v_add_u32_e32 v42, 0xffffbca0, v142
	s_waitcnt vmcnt(0) lgkmcnt(0)
	v_pk_add_f32 v[30:31], v[30:31], v[38:39]
	v_cndmask_b32_e32 v41, 0, v41, vcc
	v_cndmask_b32_e32 v42, v42, v40, vcc
	v_mov_b32_e32 v43, v41
	v_lshlrev_b64 v[42:43], 12, v[42:43]
	v_lshl_add_u64 v[42:43], s[10:11], 0, v[42:43]
	v_pk_add_f32 v[28:29], v[28:29], v[36:37]
	v_lshl_add_u64 v[42:43], v[42:43], 0, v[140:141]
	flat_store_dwordx4 v[52:53], v[28:31] offset:576
	flat_load_dwordx4 v[28:31], v[42:43]
	v_lshlrev_b64 v[36:37], 12, v[40:41]
	v_lshl_add_u64 v[36:37], s[8:9], 0, v[36:37]
	v_lshl_add_u64 v[36:37], v[36:37], 0, v[140:141]
	s_waitcnt vmcnt(0) lgkmcnt(0)
	v_pk_add_f32 v[30:31], v[34:35], v[30:31]
	v_pk_add_f32 v[28:29], v[32:33], v[28:29]
	flat_store_dwordx4 v[36:37], v[28:31]
	flat_load_dwordx4 v[28:31], v[42:43] offset:64
	s_waitcnt vmcnt(0) lgkmcnt(0)
	v_pk_add_f32 v[26:27], v[26:27], v[30:31]
	v_pk_add_f32 v[24:25], v[24:25], v[28:29]
	flat_store_dwordx4 v[36:37], v[24:27] offset:64
	flat_load_dwordx4 v[24:27], v[42:43] offset:512
	s_waitcnt vmcnt(0) lgkmcnt(0)
	v_pk_add_f32 v[22:23], v[22:23], v[26:27]
	v_pk_add_f32 v[20:21], v[20:21], v[24:25]
	flat_store_dwordx4 v[36:37], v[20:23] offset:512
	flat_load_dwordx4 v[20:23], v[42:43] offset:576
	v_add_u32_e32 v24, 0xb0, v142
	v_ashrrev_i32_e32 v25, 31, v24
	v_cmp_gt_i32_e32 vcc, s45, v24
	v_add_u32_e32 v26, 0xffffbcb0, v142
	s_waitcnt vmcnt(0) lgkmcnt(0)
	v_pk_add_f32 v[14:15], v[14:15], v[22:23]
	v_cndmask_b32_e32 v25, 0, v25, vcc
	v_cndmask_b32_e32 v26, v26, v24, vcc
	v_mov_b32_e32 v27, v25
	v_lshlrev_b64 v[26:27], 12, v[26:27]
	v_lshl_add_u64 v[26:27], s[10:11], 0, v[26:27]
	v_pk_add_f32 v[12:13], v[12:13], v[20:21]
	v_lshl_add_u64 v[26:27], v[26:27], 0, v[140:141]
	flat_store_dwordx4 v[36:37], v[12:15] offset:576
	flat_load_dwordx4 v[12:15], v[26:27]
	v_lshlrev_b64 v[20:21], 12, v[24:25]
	v_lshl_add_u64 v[20:21], s[8:9], 0, v[20:21]
	v_lshl_add_u64 v[20:21], v[20:21], 0, v[140:141]
	s_andn2_b64 vcc, exec, s[4:5]
	s_mov_b64 s[4:5], -1
	s_waitcnt vmcnt(0) lgkmcnt(0)
	v_pk_add_f32 v[14:15], v[18:19], v[14:15]
	v_pk_add_f32 v[12:13], v[16:17], v[12:13]
	flat_store_dwordx4 v[20:21], v[12:15]
	flat_load_dwordx4 v[12:15], v[26:27] offset:64
	s_waitcnt vmcnt(0) lgkmcnt(0)
	v_pk_add_f32 v[10:11], v[10:11], v[14:15]
	v_pk_add_f32 v[8:9], v[8:9], v[12:13]
	flat_store_dwordx4 v[20:21], v[8:11] offset:64
	flat_load_dwordx4 v[8:11], v[26:27] offset:512
	s_waitcnt vmcnt(0) lgkmcnt(0)
	v_pk_add_f32 v[6:7], v[6:7], v[10:11]
	v_pk_add_f32 v[4:5], v[4:5], v[8:9]
	flat_store_dwordx4 v[20:21], v[4:7] offset:512
	flat_load_dwordx4 v[4:7], v[26:27] offset:576
	s_waitcnt vmcnt(0) lgkmcnt(0)
	v_pk_add_f32 v[2:3], v[2:3], v[6:7]
	v_pk_add_f32 v[0:1], v[0:1], v[4:5]
	flat_store_dwordx4 v[20:21], v[0:3] offset:576
	s_cbranch_vccnz .LBB0_1058
	s_andn2_b64 vcc, exec, s[6:7]
	s_cbranch_vccnz .LBB0_1057
	s_barrier
	s_branch .LBB0_1057
.LBB0_1068:
	s_and_b32 s60, s2, 7
	s_lshr_b32 s61, s2, 3
	s_lshl_b32 s60, s60, 3
	s_lshr_b32 s62, s61, 2
	s_add_i32 s60, s60, s62
	s_and_b32 s61, s61, 3
	s_mul_i32 s62, s60, 0x110
	s_addk_i32 s62, 0x100
	v_lshrrev_b32_e32 v0, 6, v201
	s_nop 0
	v_readfirstlane_b32 s63, v0
	s_lshl_b32 s66, s62, 12
	s_add_u32 s64, s0, s66
	s_addc_u32 s65, s1, 0
	s_lshl_b32 s68, s61, 8
	s_lshl_b32 s69, s63, 5
	s_add_i32 s68, s68, s69
	s_lshl_b32 s69, s68, 12
	s_add_u32 s66, s34, s69
	s_addc_u32 s67, s35, 0
	s_lshl_b32 s69, s62, 12
	s_lshl_b32 s74, s68, 2
	s_add_u32 s69, s69, s74
	s_add_u32 s70, s10, s69
	s_addc_u32 s71, s11, 0
	s_add_u32 s72, s8, s69
	s_addc_u32 s73, s9, 0
	v_and_b32_e32 v209, 15, v200
	v_lshrrev_b32_e32 v210, 4, v200
	v_lshlrev_b32_e32 v211, 12, v209
	v_lshl_add_u32 v213, v210, 4, v211
	v_lshl_add_u32 v211, v210, 6, v211
	v_add_u32_e32 v212, 0x10000, v211
	v_mov_b32_e32 v192, 0
	v_mov_b32_e32 v193, 0
	v_mov_b32_e32 v194, 0
	v_mov_b32_e32 v195, 0
	v_mov_b32_e32 v196, 0
	v_mov_b32_e32 v197, 0
	v_mov_b32_e32 v198, 0
	v_mov_b32_e32 v199, 0
	global_load_dwordx4 v[214:217], v213, s[70:71]
	global_load_dwordx4 v[218:221], v213, s[70:71] offset:64
	global_load_dwordx4 v[0:3], v211, s[64:65] offset:0
	global_load_dwordx4 v[16:19], v211, s[66:67] offset:0
	global_load_dwordx4 v[32:35], v212, s[66:67] offset:0
	global_load_dwordx4 v[4:7], v211, s[64:65] offset:16
	global_load_dwordx4 v[20:23], v211, s[66:67] offset:16
	global_load_dwordx4 v[36:39], v212, s[66:67] offset:16
	global_load_dwordx4 v[8:11], v211, s[64:65] offset:32
	global_load_dwordx4 v[24:27], v211, s[66:67] offset:32
	global_load_dwordx4 v[40:43], v212, s[66:67] offset:32
	global_load_dwordx4 v[12:15], v211, s[64:65] offset:48
	global_load_dwordx4 v[28:31], v211, s[66:67] offset:48
	global_load_dwordx4 v[44:47], v212, s[66:67] offset:48
	global_load_dwordx4 v[48:51], v211, s[64:65] offset:256
	global_load_dwordx4 v[64:67], v211, s[66:67] offset:256
	global_load_dwordx4 v[80:83], v212, s[66:67] offset:256
	global_load_dwordx4 v[52:55], v211, s[64:65] offset:272
	global_load_dwordx4 v[68:71], v211, s[66:67] offset:272
	global_load_dwordx4 v[84:87], v212, s[66:67] offset:272
	global_load_dwordx4 v[56:59], v211, s[64:65] offset:288
	global_load_dwordx4 v[72:75], v211, s[66:67] offset:288
	global_load_dwordx4 v[88:91], v212, s[66:67] offset:288
	global_load_dwordx4 v[60:63], v211, s[64:65] offset:304
	global_load_dwordx4 v[76:79], v211, s[66:67] offset:304
	global_load_dwordx4 v[92:95], v212, s[66:67] offset:304
	global_load_dwordx4 v[96:99], v211, s[64:65] offset:512
	global_load_dwordx4 v[112:115], v211, s[66:67] offset:512
	global_load_dwordx4 v[128:131], v212, s[66:67] offset:512
	global_load_dwordx4 v[100:103], v211, s[64:65] offset:528
	global_load_dwordx4 v[116:119], v211, s[66:67] offset:528
	global_load_dwordx4 v[132:135], v212, s[66:67] offset:528
	global_load_dwordx4 v[104:107], v211, s[64:65] offset:544
	global_load_dwordx4 v[120:123], v211, s[66:67] offset:544
	global_load_dwordx4 v[136:139], v212, s[66:67] offset:544
	global_load_dwordx4 v[108:111], v211, s[64:65] offset:560
	global_load_dwordx4 v[124:127], v211, s[66:67] offset:560
	global_load_dwordx4 v[140:143], v212, s[66:67] offset:560
	global_load_dwordx4 v[144:147], v211, s[64:65] offset:768
	global_load_dwordx4 v[160:163], v211, s[66:67] offset:768
	global_load_dwordx4 v[176:179], v212, s[66:67] offset:768
	global_load_dwordx4 v[148:151], v211, s[64:65] offset:784
	global_load_dwordx4 v[164:167], v211, s[66:67] offset:784
	global_load_dwordx4 v[180:183], v212, s[66:67] offset:784
	global_load_dwordx4 v[152:155], v211, s[64:65] offset:800
	global_load_dwordx4 v[168:171], v211, s[66:67] offset:800
	global_load_dwordx4 v[184:187], v212, s[66:67] offset:800
	global_load_dwordx4 v[156:159], v211, s[64:65] offset:816
	global_load_dwordx4 v[172:175], v211, s[66:67] offset:816
	global_load_dwordx4 v[188:191], v212, s[66:67] offset:816
	s_waitcnt vmcnt(36)
	v_mfma_f32_16x16x32_bf16 v[192:195], v[16:19], v[0:3], v[192:195]
	v_mfma_f32_16x16x32_bf16 v[196:199], v[32:35], v[0:3], v[196:199]
	v_mfma_f32_16x16x32_bf16 v[192:195], v[20:23], v[4:7], v[192:195]
	v_mfma_f32_16x16x32_bf16 v[196:199], v[36:39], v[4:7], v[196:199]
	v_mfma_f32_16x16x32_bf16 v[192:195], v[24:27], v[8:11], v[192:195]
	v_mfma_f32_16x16x32_bf16 v[196:199], v[40:43], v[8:11], v[196:199]
	v_mfma_f32_16x16x32_bf16 v[192:195], v[28:31], v[12:15], v[192:195]
	v_mfma_f32_16x16x32_bf16 v[196:199], v[44:47], v[12:15], v[196:199]
	global_load_dwordx4 v[0:3], v211, s[64:65] offset:1024
	global_load_dwordx4 v[16:19], v211, s[66:67] offset:1024
	global_load_dwordx4 v[32:35], v212, s[66:67] offset:1024
	global_load_dwordx4 v[4:7], v211, s[64:65] offset:1040
	global_load_dwordx4 v[20:23], v211, s[66:67] offset:1040
	global_load_dwordx4 v[36:39], v212, s[66:67] offset:1040
	global_load_dwordx4 v[8:11], v211, s[64:65] offset:1056
	global_load_dwordx4 v[24:27], v211, s[66:67] offset:1056
	global_load_dwordx4 v[40:43], v212, s[66:67] offset:1056
	global_load_dwordx4 v[12:15], v211, s[64:65] offset:1072
	global_load_dwordx4 v[28:31], v211, s[66:67] offset:1072
	global_load_dwordx4 v[44:47], v212, s[66:67] offset:1072
	s_waitcnt vmcnt(36)
	v_mfma_f32_16x16x32_bf16 v[192:195], v[64:67], v[48:51], v[192:195]
	v_mfma_f32_16x16x32_bf16 v[196:199], v[80:83], v[48:51], v[196:199]
	v_mfma_f32_16x16x32_bf16 v[192:195], v[68:71], v[52:55], v[192:195]
	v_mfma_f32_16x16x32_bf16 v[196:199], v[84:87], v[52:55], v[196:199]
	v_mfma_f32_16x16x32_bf16 v[192:195], v[72:75], v[56:59], v[192:195]
	v_mfma_f32_16x16x32_bf16 v[196:199], v[88:91], v[56:59], v[196:199]
	v_mfma_f32_16x16x32_bf16 v[192:195], v[76:79], v[60:63], v[192:195]
	v_mfma_f32_16x16x32_bf16 v[196:199], v[92:95], v[60:63], v[196:199]
	global_load_dwordx4 v[48:51], v211, s[64:65] offset:1280
	global_load_dwordx4 v[64:67], v211, s[66:67] offset:1280
	global_load_dwordx4 v[80:83], v212, s[66:67] offset:1280
	global_load_dwordx4 v[52:55], v211, s[64:65] offset:1296
	global_load_dwordx4 v[68:71], v211, s[66:67] offset:1296
	global_load_dwordx4 v[84:87], v212, s[66:67] offset:1296
	global_load_dwordx4 v[56:59], v211, s[64:65] offset:1312
	global_load_dwordx4 v[72:75], v211, s[66:67] offset:1312
	global_load_dwordx4 v[88:91], v212, s[66:67] offset:1312
	global_load_dwordx4 v[60:63], v211, s[64:65] offset:1328
	global_load_dwordx4 v[76:79], v211, s[66:67] offset:1328
	global_load_dwordx4 v[92:95], v212, s[66:67] offset:1328
	s_waitcnt vmcnt(36)
	v_mfma_f32_16x16x32_bf16 v[192:195], v[112:115], v[96:99], v[192:195]
	v_mfma_f32_16x16x32_bf16 v[196:199], v[128:131], v[96:99], v[196:199]
	v_mfma_f32_16x16x32_bf16 v[192:195], v[116:119], v[100:103], v[192:195]
	v_mfma_f32_16x16x32_bf16 v[196:199], v[132:135], v[100:103], v[196:199]
	v_mfma_f32_16x16x32_bf16 v[192:195], v[120:123], v[104:107], v[192:195]
	v_mfma_f32_16x16x32_bf16 v[196:199], v[136:139], v[104:107], v[196:199]
	v_mfma_f32_16x16x32_bf16 v[192:195], v[124:127], v[108:111], v[192:195]
	v_mfma_f32_16x16x32_bf16 v[196:199], v[140:143], v[108:111], v[196:199]
	global_load_dwordx4 v[96:99], v211, s[64:65] offset:1536
	global_load_dwordx4 v[112:115], v211, s[66:67] offset:1536
	global_load_dwordx4 v[128:131], v212, s[66:67] offset:1536
	global_load_dwordx4 v[100:103], v211, s[64:65] offset:1552
	global_load_dwordx4 v[116:119], v211, s[66:67] offset:1552
	global_load_dwordx4 v[132:135], v212, s[66:67] offset:1552
	global_load_dwordx4 v[104:107], v211, s[64:65] offset:1568
	global_load_dwordx4 v[120:123], v211, s[66:67] offset:1568
	global_load_dwordx4 v[136:139], v212, s[66:67] offset:1568
	global_load_dwordx4 v[108:111], v211, s[64:65] offset:1584
	global_load_dwordx4 v[124:127], v211, s[66:67] offset:1584
	global_load_dwordx4 v[140:143], v212, s[66:67] offset:1584
	s_waitcnt vmcnt(36)
	v_mfma_f32_16x16x32_bf16 v[192:195], v[160:163], v[144:147], v[192:195]
	v_mfma_f32_16x16x32_bf16 v[196:199], v[176:179], v[144:147], v[196:199]
	v_mfma_f32_16x16x32_bf16 v[192:195], v[164:167], v[148:151], v[192:195]
	v_mfma_f32_16x16x32_bf16 v[196:199], v[180:183], v[148:151], v[196:199]
	v_mfma_f32_16x16x32_bf16 v[192:195], v[168:171], v[152:155], v[192:195]
	v_mfma_f32_16x16x32_bf16 v[196:199], v[184:187], v[152:155], v[196:199]
	v_mfma_f32_16x16x32_bf16 v[192:195], v[172:175], v[156:159], v[192:195]
	v_mfma_f32_16x16x32_bf16 v[196:199], v[188:191], v[156:159], v[196:199]
	global_load_dwordx4 v[144:147], v211, s[64:65] offset:1792
	global_load_dwordx4 v[160:163], v211, s[66:67] offset:1792
	global_load_dwordx4 v[176:179], v212, s[66:67] offset:1792
	global_load_dwordx4 v[148:151], v211, s[64:65] offset:1808
	global_load_dwordx4 v[164:167], v211, s[66:67] offset:1808
	global_load_dwordx4 v[180:183], v212, s[66:67] offset:1808
	global_load_dwordx4 v[152:155], v211, s[64:65] offset:1824
	global_load_dwordx4 v[168:171], v211, s[66:67] offset:1824
	global_load_dwordx4 v[184:187], v212, s[66:67] offset:1824
	global_load_dwordx4 v[156:159], v211, s[64:65] offset:1840
	global_load_dwordx4 v[172:175], v211, s[66:67] offset:1840
	global_load_dwordx4 v[188:191], v212, s[66:67] offset:1840
	s_waitcnt vmcnt(36)
	v_mfma_f32_16x16x32_bf16 v[192:195], v[16:19], v[0:3], v[192:195]
	v_mfma_f32_16x16x32_bf16 v[196:199], v[32:35], v[0:3], v[196:199]
	v_mfma_f32_16x16x32_bf16 v[192:195], v[20:23], v[4:7], v[192:195]
	v_mfma_f32_16x16x32_bf16 v[196:199], v[36:39], v[4:7], v[196:199]
	v_mfma_f32_16x16x32_bf16 v[192:195], v[24:27], v[8:11], v[192:195]
	v_mfma_f32_16x16x32_bf16 v[196:199], v[40:43], v[8:11], v[196:199]
	v_mfma_f32_16x16x32_bf16 v[192:195], v[28:31], v[12:15], v[192:195]
	v_mfma_f32_16x16x32_bf16 v[196:199], v[44:47], v[12:15], v[196:199]
	global_load_dwordx4 v[0:3], v211, s[64:65] offset:2048
	global_load_dwordx4 v[16:19], v211, s[66:67] offset:2048
	global_load_dwordx4 v[32:35], v212, s[66:67] offset:2048
	global_load_dwordx4 v[4:7], v211, s[64:65] offset:2064
	global_load_dwordx4 v[20:23], v211, s[66:67] offset:2064
	global_load_dwordx4 v[36:39], v212, s[66:67] offset:2064
	global_load_dwordx4 v[8:11], v211, s[64:65] offset:2080
	global_load_dwordx4 v[24:27], v211, s[66:67] offset:2080
	global_load_dwordx4 v[40:43], v212, s[66:67] offset:2080
	global_load_dwordx4 v[12:15], v211, s[64:65] offset:2096
	global_load_dwordx4 v[28:31], v211, s[66:67] offset:2096
	global_load_dwordx4 v[44:47], v212, s[66:67] offset:2096
	s_waitcnt vmcnt(36)
	v_mfma_f32_16x16x32_bf16 v[192:195], v[64:67], v[48:51], v[192:195]
	v_mfma_f32_16x16x32_bf16 v[196:199], v[80:83], v[48:51], v[196:199]
	v_mfma_f32_16x16x32_bf16 v[192:195], v[68:71], v[52:55], v[192:195]
	v_mfma_f32_16x16x32_bf16 v[196:199], v[84:87], v[52:55], v[196:199]
	v_mfma_f32_16x16x32_bf16 v[192:195], v[72:75], v[56:59], v[192:195]
	v_mfma_f32_16x16x32_bf16 v[196:199], v[88:91], v[56:59], v[196:199]
	v_mfma_f32_16x16x32_bf16 v[192:195], v[76:79], v[60:63], v[192:195]
	v_mfma_f32_16x16x32_bf16 v[196:199], v[92:95], v[60:63], v[196:199]
	global_load_dwordx4 v[48:51], v211, s[64:65] offset:2304
	global_load_dwordx4 v[64:67], v211, s[66:67] offset:2304
	global_load_dwordx4 v[80:83], v212, s[66:67] offset:2304
	global_load_dwordx4 v[52:55], v211, s[64:65] offset:2320
	global_load_dwordx4 v[68:71], v211, s[66:67] offset:2320
	global_load_dwordx4 v[84:87], v212, s[66:67] offset:2320
	global_load_dwordx4 v[56:59], v211, s[64:65] offset:2336
	global_load_dwordx4 v[72:75], v211, s[66:67] offset:2336
	global_load_dwordx4 v[88:91], v212, s[66:67] offset:2336
	global_load_dwordx4 v[60:63], v211, s[64:65] offset:2352
	global_load_dwordx4 v[76:79], v211, s[66:67] offset:2352
	global_load_dwordx4 v[92:95], v212, s[66:67] offset:2352
	s_waitcnt vmcnt(36)
	v_mfma_f32_16x16x32_bf16 v[192:195], v[112:115], v[96:99], v[192:195]
	v_mfma_f32_16x16x32_bf16 v[196:199], v[128:131], v[96:99], v[196:199]
	v_mfma_f32_16x16x32_bf16 v[192:195], v[116:119], v[100:103], v[192:195]
	v_mfma_f32_16x16x32_bf16 v[196:199], v[132:135], v[100:103], v[196:199]
	v_mfma_f32_16x16x32_bf16 v[192:195], v[120:123], v[104:107], v[192:195]
	v_mfma_f32_16x16x32_bf16 v[196:199], v[136:139], v[104:107], v[196:199]
	v_mfma_f32_16x16x32_bf16 v[192:195], v[124:127], v[108:111], v[192:195]
	v_mfma_f32_16x16x32_bf16 v[196:199], v[140:143], v[108:111], v[196:199]
	global_load_dwordx4 v[96:99], v211, s[64:65] offset:2560
	global_load_dwordx4 v[112:115], v211, s[66:67] offset:2560
	global_load_dwordx4 v[128:131], v212, s[66:67] offset:2560
	global_load_dwordx4 v[100:103], v211, s[64:65] offset:2576
	global_load_dwordx4 v[116:119], v211, s[66:67] offset:2576
	global_load_dwordx4 v[132:135], v212, s[66:67] offset:2576
	global_load_dwordx4 v[104:107], v211, s[64:65] offset:2592
	global_load_dwordx4 v[120:123], v211, s[66:67] offset:2592
	global_load_dwordx4 v[136:139], v212, s[66:67] offset:2592
	global_load_dwordx4 v[108:111], v211, s[64:65] offset:2608
	global_load_dwordx4 v[124:127], v211, s[66:67] offset:2608
	global_load_dwordx4 v[140:143], v212, s[66:67] offset:2608
	s_waitcnt vmcnt(36)
	v_mfma_f32_16x16x32_bf16 v[192:195], v[160:163], v[144:147], v[192:195]
	v_mfma_f32_16x16x32_bf16 v[196:199], v[176:179], v[144:147], v[196:199]
	v_mfma_f32_16x16x32_bf16 v[192:195], v[164:167], v[148:151], v[192:195]
	v_mfma_f32_16x16x32_bf16 v[196:199], v[180:183], v[148:151], v[196:199]
	v_mfma_f32_16x16x32_bf16 v[192:195], v[168:171], v[152:155], v[192:195]
	v_mfma_f32_16x16x32_bf16 v[196:199], v[184:187], v[152:155], v[196:199]
	v_mfma_f32_16x16x32_bf16 v[192:195], v[172:175], v[156:159], v[192:195]
	v_mfma_f32_16x16x32_bf16 v[196:199], v[188:191], v[156:159], v[196:199]
	global_load_dwordx4 v[144:147], v211, s[64:65] offset:2816
	global_load_dwordx4 v[160:163], v211, s[66:67] offset:2816
	global_load_dwordx4 v[176:179], v212, s[66:67] offset:2816
	global_load_dwordx4 v[148:151], v211, s[64:65] offset:2832
	global_load_dwordx4 v[164:167], v211, s[66:67] offset:2832
	global_load_dwordx4 v[180:183], v212, s[66:67] offset:2832
	global_load_dwordx4 v[152:155], v211, s[64:65] offset:2848
	global_load_dwordx4 v[168:171], v211, s[66:67] offset:2848
	global_load_dwordx4 v[184:187], v212, s[66:67] offset:2848
	global_load_dwordx4 v[156:159], v211, s[64:65] offset:2864
	global_load_dwordx4 v[172:175], v211, s[66:67] offset:2864
	global_load_dwordx4 v[188:191], v212, s[66:67] offset:2864
	s_waitcnt vmcnt(36)
	v_mfma_f32_16x16x32_bf16 v[192:195], v[16:19], v[0:3], v[192:195]
	v_mfma_f32_16x16x32_bf16 v[196:199], v[32:35], v[0:3], v[196:199]
	v_mfma_f32_16x16x32_bf16 v[192:195], v[20:23], v[4:7], v[192:195]
	v_mfma_f32_16x16x32_bf16 v[196:199], v[36:39], v[4:7], v[196:199]
	v_mfma_f32_16x16x32_bf16 v[192:195], v[24:27], v[8:11], v[192:195]
	v_mfma_f32_16x16x32_bf16 v[196:199], v[40:43], v[8:11], v[196:199]
	v_mfma_f32_16x16x32_bf16 v[192:195], v[28:31], v[12:15], v[192:195]
	v_mfma_f32_16x16x32_bf16 v[196:199], v[44:47], v[12:15], v[196:199]
	global_load_dwordx4 v[0:3], v211, s[64:65] offset:3072
	global_load_dwordx4 v[16:19], v211, s[66:67] offset:3072
	global_load_dwordx4 v[32:35], v212, s[66:67] offset:3072
	global_load_dwordx4 v[4:7], v211, s[64:65] offset:3088
	global_load_dwordx4 v[20:23], v211, s[66:67] offset:3088
	global_load_dwordx4 v[36:39], v212, s[66:67] offset:3088
	global_load_dwordx4 v[8:11], v211, s[64:65] offset:3104
	global_load_dwordx4 v[24:27], v211, s[66:67] offset:3104
	global_load_dwordx4 v[40:43], v212, s[66:67] offset:3104
	global_load_dwordx4 v[12:15], v211, s[64:65] offset:3120
	global_load_dwordx4 v[28:31], v211, s[66:67] offset:3120
	global_load_dwordx4 v[44:47], v212, s[66:67] offset:3120
	s_waitcnt vmcnt(36)
	v_mfma_f32_16x16x32_bf16 v[192:195], v[64:67], v[48:51], v[192:195]
	v_mfma_f32_16x16x32_bf16 v[196:199], v[80:83], v[48:51], v[196:199]
	v_mfma_f32_16x16x32_bf16 v[192:195], v[68:71], v[52:55], v[192:195]
	v_mfma_f32_16x16x32_bf16 v[196:199], v[84:87], v[52:55], v[196:199]
	v_mfma_f32_16x16x32_bf16 v[192:195], v[72:75], v[56:59], v[192:195]
	v_mfma_f32_16x16x32_bf16 v[196:199], v[88:91], v[56:59], v[196:199]
	v_mfma_f32_16x16x32_bf16 v[192:195], v[76:79], v[60:63], v[192:195]
	v_mfma_f32_16x16x32_bf16 v[196:199], v[92:95], v[60:63], v[196:199]
	global_load_dwordx4 v[48:51], v211, s[64:65] offset:3328
	global_load_dwordx4 v[64:67], v211, s[66:67] offset:3328
	global_load_dwordx4 v[80:83], v212, s[66:67] offset:3328
	global_load_dwordx4 v[52:55], v211, s[64:65] offset:3344
	global_load_dwordx4 v[68:71], v211, s[66:67] offset:3344
	global_load_dwordx4 v[84:87], v212, s[66:67] offset:3344
	global_load_dwordx4 v[56:59], v211, s[64:65] offset:3360
	global_load_dwordx4 v[72:75], v211, s[66:67] offset:3360
	global_load_dwordx4 v[88:91], v212, s[66:67] offset:3360
	global_load_dwordx4 v[60:63], v211, s[64:65] offset:3376
	global_load_dwordx4 v[76:79], v211, s[66:67] offset:3376
	global_load_dwordx4 v[92:95], v212, s[66:67] offset:3376
	s_waitcnt vmcnt(36)
	v_mfma_f32_16x16x32_bf16 v[192:195], v[112:115], v[96:99], v[192:195]
	v_mfma_f32_16x16x32_bf16 v[196:199], v[128:131], v[96:99], v[196:199]
	v_mfma_f32_16x16x32_bf16 v[192:195], v[116:119], v[100:103], v[192:195]
	v_mfma_f32_16x16x32_bf16 v[196:199], v[132:135], v[100:103], v[196:199]
	v_mfma_f32_16x16x32_bf16 v[192:195], v[120:123], v[104:107], v[192:195]
	v_mfma_f32_16x16x32_bf16 v[196:199], v[136:139], v[104:107], v[196:199]
	v_mfma_f32_16x16x32_bf16 v[192:195], v[124:127], v[108:111], v[192:195]
	v_mfma_f32_16x16x32_bf16 v[196:199], v[140:143], v[108:111], v[196:199]
	global_load_dwordx4 v[96:99], v211, s[64:65] offset:3584
	global_load_dwordx4 v[112:115], v211, s[66:67] offset:3584
	global_load_dwordx4 v[128:131], v212, s[66:67] offset:3584
	global_load_dwordx4 v[100:103], v211, s[64:65] offset:3600
	global_load_dwordx4 v[116:119], v211, s[66:67] offset:3600
	global_load_dwordx4 v[132:135], v212, s[66:67] offset:3600
	global_load_dwordx4 v[104:107], v211, s[64:65] offset:3616
	global_load_dwordx4 v[120:123], v211, s[66:67] offset:3616
	global_load_dwordx4 v[136:139], v212, s[66:67] offset:3616
	global_load_dwordx4 v[108:111], v211, s[64:65] offset:3632
	global_load_dwordx4 v[124:127], v211, s[66:67] offset:3632
	global_load_dwordx4 v[140:143], v212, s[66:67] offset:3632
	s_waitcnt vmcnt(36)
	v_mfma_f32_16x16x32_bf16 v[192:195], v[160:163], v[144:147], v[192:195]
	v_mfma_f32_16x16x32_bf16 v[196:199], v[176:179], v[144:147], v[196:199]
	v_mfma_f32_16x16x32_bf16 v[192:195], v[164:167], v[148:151], v[192:195]
	v_mfma_f32_16x16x32_bf16 v[196:199], v[180:183], v[148:151], v[196:199]
	v_mfma_f32_16x16x32_bf16 v[192:195], v[168:171], v[152:155], v[192:195]
	v_mfma_f32_16x16x32_bf16 v[196:199], v[184:187], v[152:155], v[196:199]
	v_mfma_f32_16x16x32_bf16 v[192:195], v[172:175], v[156:159], v[192:195]
	v_mfma_f32_16x16x32_bf16 v[196:199], v[188:191], v[156:159], v[196:199]
	global_load_dwordx4 v[144:147], v211, s[64:65] offset:3840
	global_load_dwordx4 v[160:163], v211, s[66:67] offset:3840
	global_load_dwordx4 v[176:179], v212, s[66:67] offset:3840
	global_load_dwordx4 v[148:151], v211, s[64:65] offset:3856
	global_load_dwordx4 v[164:167], v211, s[66:67] offset:3856
	global_load_dwordx4 v[180:183], v212, s[66:67] offset:3856
	global_load_dwordx4 v[152:155], v211, s[64:65] offset:3872
	global_load_dwordx4 v[168:171], v211, s[66:67] offset:3872
	global_load_dwordx4 v[184:187], v212, s[66:67] offset:3872
	global_load_dwordx4 v[156:159], v211, s[64:65] offset:3888
	global_load_dwordx4 v[172:175], v211, s[66:67] offset:3888
	global_load_dwordx4 v[188:191], v212, s[66:67] offset:3888
	s_waitcnt vmcnt(36)
	v_mfma_f32_16x16x32_bf16 v[192:195], v[16:19], v[0:3], v[192:195]
	v_mfma_f32_16x16x32_bf16 v[196:199], v[32:35], v[0:3], v[196:199]
	v_mfma_f32_16x16x32_bf16 v[192:195], v[20:23], v[4:7], v[192:195]
	v_mfma_f32_16x16x32_bf16 v[196:199], v[36:39], v[4:7], v[196:199]
	v_mfma_f32_16x16x32_bf16 v[192:195], v[24:27], v[8:11], v[192:195]
	v_mfma_f32_16x16x32_bf16 v[196:199], v[40:43], v[8:11], v[196:199]
	v_mfma_f32_16x16x32_bf16 v[192:195], v[28:31], v[12:15], v[192:195]
	v_mfma_f32_16x16x32_bf16 v[196:199], v[44:47], v[12:15], v[196:199]
	s_waitcnt vmcnt(24)
	v_mfma_f32_16x16x32_bf16 v[192:195], v[64:67], v[48:51], v[192:195]
	v_mfma_f32_16x16x32_bf16 v[196:199], v[80:83], v[48:51], v[196:199]
	v_mfma_f32_16x16x32_bf16 v[192:195], v[68:71], v[52:55], v[192:195]
	v_mfma_f32_16x16x32_bf16 v[196:199], v[84:87], v[52:55], v[196:199]
	v_mfma_f32_16x16x32_bf16 v[192:195], v[72:75], v[56:59], v[192:195]
	v_mfma_f32_16x16x32_bf16 v[196:199], v[88:91], v[56:59], v[196:199]
	v_mfma_f32_16x16x32_bf16 v[192:195], v[76:79], v[60:63], v[192:195]
	v_mfma_f32_16x16x32_bf16 v[196:199], v[92:95], v[60:63], v[196:199]
	s_waitcnt vmcnt(12)
	v_mfma_f32_16x16x32_bf16 v[192:195], v[112:115], v[96:99], v[192:195]
	v_mfma_f32_16x16x32_bf16 v[196:199], v[128:131], v[96:99], v[196:199]
	v_mfma_f32_16x16x32_bf16 v[192:195], v[116:119], v[100:103], v[192:195]
	v_mfma_f32_16x16x32_bf16 v[196:199], v[132:135], v[100:103], v[196:199]
	v_mfma_f32_16x16x32_bf16 v[192:195], v[120:123], v[104:107], v[192:195]
	v_mfma_f32_16x16x32_bf16 v[196:199], v[136:139], v[104:107], v[196:199]
	v_mfma_f32_16x16x32_bf16 v[192:195], v[124:127], v[108:111], v[192:195]
	v_mfma_f32_16x16x32_bf16 v[196:199], v[140:143], v[108:111], v[196:199]
	s_waitcnt vmcnt(0)
	v_mfma_f32_16x16x32_bf16 v[192:195], v[160:163], v[144:147], v[192:195]
	v_mfma_f32_16x16x32_bf16 v[196:199], v[176:179], v[144:147], v[196:199]
	v_mfma_f32_16x16x32_bf16 v[192:195], v[164:167], v[148:151], v[192:195]
	v_mfma_f32_16x16x32_bf16 v[196:199], v[180:183], v[148:151], v[196:199]
	v_mfma_f32_16x16x32_bf16 v[192:195], v[168:171], v[152:155], v[192:195]
	v_mfma_f32_16x16x32_bf16 v[196:199], v[184:187], v[152:155], v[196:199]
	v_mfma_f32_16x16x32_bf16 v[192:195], v[172:175], v[156:159], v[192:195]
	v_mfma_f32_16x16x32_bf16 v[196:199], v[188:191], v[156:159], v[196:199]
	s_waitcnt vmcnt(0)
	s_nop 15
	s_nop 15
	v_pk_add_f32 v[192:193], v[214:215], v[192:193]
	v_pk_add_f32 v[194:195], v[216:217], v[194:195]
	v_pk_add_f32 v[196:197], v[218:219], v[196:197]
	v_pk_add_f32 v[198:199], v[220:221], v[198:199]
	global_store_dwordx4 v213, v[192:195], s[72:73]
	global_store_dwordx4 v213, v[196:199], s[72:73] offset:64
	s_waitcnt vmcnt(0)
	s_barrier
